# P0 pre-norm loop hand-written with next-iteration prefetch + convert_p loads issued up front; on top of conv rewrite
# speedup vs baseline: 1.0265x; 1.0011x over previous
; DEV int tidx() { int t = threadIdx.x; asm volatile("" : "+v"(t)); return t; }
; DEV int bidx() { int t = blockIdx.x; asm volatile("" : "+s"(t)); return t; }
; DEV unsigned cvt_pk_bf16(float lo, float hi) { const f32x2_ v = {lo, hi}; return __builtin_bit_cast(unsigned, __builtin_convertvector(v, bf16x2n_)); }
; DEV void convert_p(const Params& p, int l) {
;   bf16_t* Pb = (bf16_t*)(p.ws + WS_Z + ZO_PB);
;   const int gtid = bidx() * 512 + tidx(), gstride = gridDim.x * 512;
;   for (int c = gtid; c < MTOK * 64; c += gstride) {
;     const int row = c >> 6, c4 = (c & 63) * 4;
;     const float* src = row < TP ? p.in[I_PP] + ((size_t)l * TP + row) * DPLE + c4 : p.in[I_PS] + ((size_t)l * TS + (row - TP)) * DPLE + c4;
;     const f32x4 v = *(const f32x4*)src;
;     u32x2 w; w.x = cvt_pk_bf16(v[0], v[1]); w.y = cvt_pk_bf16(v[2], v[3]);
;     *(u32x2*)(Pb + (size_t)row * DPLE + c4) = w;
;   }
; }
.LBB0_239:
	s_or_b64 exec, exec, s[2:3]
	s_mov_b32 s6, s74
	v_mov_b32_e32 v0, v171
	s_mov_b32 s0, 0x110000
	v_lshl_add_u32 v1, s6, 9, v0
	v_cmp_gt_i32_e32 vcc, s0, v1
	s_and_saveexec_b64 s[0:1], vcc
	s_cbranch_execz .LBB0_246
	v_readlane_b32 s4, v248, 43
	s_mov_b32 s12, s4
	s_mov_b32 s8, s12
	v_readlane_b32 s5, v248, 44
	v_writelane_b32 v248, s8, 43
	s_add_u32 s2, s28, 0x11300000
	s_addc_u32 s3, s29, 0
	v_writelane_b32 v248, s9, 44
	s_ashr_i32 s13, s4, 31
	v_readlane_b32 s36, v248, 20
	s_lshl_b64 s[4:5], s[12:13], 20
	s_lshl_b64 s[8:9], s[12:13], 24
	v_readlane_b32 s42, v248, 26
	v_readlane_b32 s43, v248, 27
	s_add_u32 s4, s42, s4
	v_readlane_b32 s40, v248, 24
	s_addc_u32 s5, s43, s5
	v_readlane_b32 s41, v248, 25
	s_add_u32 s8, s40, s8
	v_lshlrev_b32_e32 v0, 2, v0
	s_addc_u32 s9, s41, s9
	v_lshl_add_u32 v6, s6, 11, v0
	s_mov_b64 s[12:13], 0
	v_readlane_b32 s37, v248, 21
	v_readlane_b32 s38, v248, 22
	v_readlane_b32 s39, v248, 23
	v_readlane_b32 s44, v248, 28
	v_readlane_b32 s45, v248, 29
	v_readlane_b32 s46, v248, 30
	v_readlane_b32 s47, v248, 31
	v_readlane_b32 s48, v248, 32
	v_readlane_b32 s49, v248, 33
	v_readlane_b32 s50, v248, 34
	v_readlane_b32 s51, v248, 35
	v_readfirstlane_b32 s12, v1
	v_lshlrev_b32_e32 v160, 4, v202
	v_lshlrev_b32_e32 v161, 3, v202
	s_lshr_b32 s12, s12, 6
	s_lshl_b32 s13, s12, 10
	v_add_u32_e32 v162, s13, v160
	v_mov_b32_e32 v164, v162
	global_load_dwordx4 v[68:71], v162, s[8:9]
	v_add_u32_e32 v162, 0x200000, v162
	global_load_dwordx4 v[72:75], v162, s[8:9]
	v_add_u32_e32 v162, 0x200000, v162
	global_load_dwordx4 v[76:79], v162, s[8:9]
	v_add_u32_e32 v162, 0x200000, v162
	global_load_dwordx4 v[80:83], v162, s[8:9]
	v_add_u32_e32 v162, 0x200000, v162
	global_load_dwordx4 v[84:87], v162, s[8:9]
	v_add_u32_e32 v162, 0x200000, v162
	global_load_dwordx4 v[88:91], v162, s[8:9]
	v_add_u32_e32 v162, 0x200000, v162
	global_load_dwordx4 v[92:95], v162, s[8:9]
	v_add_u32_e32 v162, 0x200000, v162
	global_load_dwordx4 v[96:99], v162, s[8:9]
	s_cmp_lt_u32 s12, 0x400
	s_cselect_b32 s14, 1, 0
	s_cbranch_scc0 .Lcvp_nos
	global_load_dwordx4 v[100:103], v164, s[4:5]
.Lcvp_nos:
	s_lshl_b32 s13, s12, 9
	v_add_u32_e32 v163, s13, v161
	s_cmp_eq_u32 s14, 1
	s_cbranch_scc1 .Lcvp_w9
	s_waitcnt vmcnt(7)
	v_cvt_pk_bf16_f32 v68, v68, v69
	v_cvt_pk_bf16_f32 v69, v70, v71
	global_store_dwordx2 v163, v[68:69], s[2:3]
	v_add_u32_e32 v163, 0x100000, v163
	s_waitcnt vmcnt(7)
	v_cvt_pk_bf16_f32 v72, v72, v73
	v_cvt_pk_bf16_f32 v73, v74, v75
	global_store_dwordx2 v163, v[72:73], s[2:3]
	v_add_u32_e32 v163, 0x100000, v163
	s_waitcnt vmcnt(7)
	v_cvt_pk_bf16_f32 v76, v76, v77
	v_cvt_pk_bf16_f32 v77, v78, v79
	global_store_dwordx2 v163, v[76:77], s[2:3]
	v_add_u32_e32 v163, 0x100000, v163
	s_waitcnt vmcnt(7)
	v_cvt_pk_bf16_f32 v80, v80, v81
	v_cvt_pk_bf16_f32 v81, v82, v83
	global_store_dwordx2 v163, v[80:81], s[2:3]
	v_add_u32_e32 v163, 0x100000, v163
	s_waitcnt vmcnt(7)
	v_cvt_pk_bf16_f32 v84, v84, v85
	v_cvt_pk_bf16_f32 v85, v86, v87
	global_store_dwordx2 v163, v[84:85], s[2:3]
	v_add_u32_e32 v163, 0x100000, v163
	s_waitcnt vmcnt(7)
	v_cvt_pk_bf16_f32 v88, v88, v89
	v_cvt_pk_bf16_f32 v89, v90, v91
	global_store_dwordx2 v163, v[88:89], s[2:3]
	v_add_u32_e32 v163, 0x100000, v163
	s_waitcnt vmcnt(7)
	v_cvt_pk_bf16_f32 v92, v92, v93
	v_cvt_pk_bf16_f32 v93, v94, v95
	global_store_dwordx2 v163, v[92:93], s[2:3]
	v_add_u32_e32 v163, 0x100000, v163
	s_waitcnt vmcnt(7)
	v_cvt_pk_bf16_f32 v96, v96, v97
	v_cvt_pk_bf16_f32 v97, v98, v99
	global_store_dwordx2 v163, v[96:97], s[2:3]
	s_branch .LBB0_246
.Lcvp_w9:
	s_waitcnt vmcnt(8)
	v_cvt_pk_bf16_f32 v68, v68, v69
	v_cvt_pk_bf16_f32 v69, v70, v71
	global_store_dwordx2 v163, v[68:69], s[2:3]
	v_add_u32_e32 v163, 0x100000, v163
	s_waitcnt vmcnt(8)
	v_cvt_pk_bf16_f32 v72, v72, v73
	v_cvt_pk_bf16_f32 v73, v74, v75
	global_store_dwordx2 v163, v[72:73], s[2:3]
	v_add_u32_e32 v163, 0x100000, v163
	s_waitcnt vmcnt(8)
	v_cvt_pk_bf16_f32 v76, v76, v77
	v_cvt_pk_bf16_f32 v77, v78, v79
	global_store_dwordx2 v163, v[76:77], s[2:3]
	v_add_u32_e32 v163, 0x100000, v163
	s_waitcnt vmcnt(8)
	v_cvt_pk_bf16_f32 v80, v80, v81
	v_cvt_pk_bf16_f32 v81, v82, v83
	global_store_dwordx2 v163, v[80:81], s[2:3]
	v_add_u32_e32 v163, 0x100000, v163
	s_waitcnt vmcnt(8)
	v_cvt_pk_bf16_f32 v84, v84, v85
	v_cvt_pk_bf16_f32 v85, v86, v87
	global_store_dwordx2 v163, v[84:85], s[2:3]
	v_add_u32_e32 v163, 0x100000, v163
	s_waitcnt vmcnt(8)
	v_cvt_pk_bf16_f32 v88, v88, v89
	v_cvt_pk_bf16_f32 v89, v90, v91
	global_store_dwordx2 v163, v[88:89], s[2:3]
	v_add_u32_e32 v163, 0x100000, v163
	s_waitcnt vmcnt(8)
	v_cvt_pk_bf16_f32 v92, v92, v93
	v_cvt_pk_bf16_f32 v93, v94, v95
	global_store_dwordx2 v163, v[92:93], s[2:3]
	v_add_u32_e32 v163, 0x100000, v163
	s_waitcnt vmcnt(8)
	v_cvt_pk_bf16_f32 v96, v96, v97
	v_cvt_pk_bf16_f32 v97, v98, v99
	global_store_dwordx2 v163, v[96:97], s[2:3]
	v_add_u32_e32 v163, 0x100000, v163
	s_waitcnt vmcnt(8)
	v_cvt_pk_bf16_f32 v100, v100, v101
	v_cvt_pk_bf16_f32 v101, v102, v103
	global_store_dwordx2 v163, v[100:101], s[2:3]

; DEV int tidx() { int t = threadIdx.x; asm volatile("" : "+v"(t)); return t; }
; DEV int bidx() { int t = blockIdx.x; asm volatile("" : "+s"(t)); return t; }
; DEV void phase_p0(const Params& p, int l, unsigned char* smem) {
;     ...
;   const int lane = tidx() & 63, wid = tidx() >> 6;
;   float* X = p.out;
;   bf16_t* H = (bf16_t*)(p.ws + WS_H);
;   const float* g = p.in[I_GMIXPRE] + l * D;
;   const int nw = gridDim.x * 8;
;   for (int row = bidx() * 8 + wid; row < MTOK; row += 2 * nw) {
;     const bool v1 = row + nw < MTOK;
;     int rr[2]; rr[0] = row; rr[1] = v1 ? row + nw : row;
;     f32x4 x[2][4]; float ss[2] = {0.f, 0.f};
; #pragma unroll
;     for (int k = 0; k < 2; ++k) {
;       const int r = rr[k];
;       const float* src = (l == 0) ? (r < TP ? p.in[I_XP] + (size_t)r * D : p.in[I_XS] + (size_t)(r - TP) * D) : X + (size_t)r * D;
; #pragma unroll
;       for (int i = 0; i < 4; ++i) x[k][i] = *(const f32x4*)(src + i * 256 + lane * 4);
;     }
.LBB0_539:
	v_lshlrev_b32_e32 v0, 2, v0
	v_and_b32_e32 v32, 0xfc, v0
	v_and_b32_e32 v0, 64, v202
	v_add_u32_e32 v0, 64, v0
	v_xor_b32_e32 v1, 32, v202
	v_cmp_lt_i32_e32 vcc, v1, v0
	v_readlane_b32 s0, v248, 43
	v_readlane_b32 s1, v248, 44
	v_cndmask_b32_e32 v1, v202, v1, vcc
	v_lshlrev_b32_e32 v33, 2, v1
	v_xor_b32_e32 v1, 16, v202
	v_cmp_lt_i32_e32 vcc, v1, v0
	s_lshl_b32 s0, s0, 10
	s_ashr_i32 s1, s0, 31
	v_cndmask_b32_e32 v1, v202, v1, vcc
	v_lshlrev_b32_e32 v40, 2, v1
	v_xor_b32_e32 v1, 8, v202
	v_cmp_lt_i32_e32 vcc, v1, v0
	s_lshl_b32 s6, s6, 3
	s_lshl_b64 s[0:1], s[0:1], 2
	v_cndmask_b32_e32 v1, v202, v1, vcc
	v_lshlrev_b32_e32 v41, 2, v1
	v_xor_b32_e32 v1, 4, v202
	v_cmp_lt_i32_e32 vcc, v1, v0
	s_add_u32 s0, s76, s0
	s_addc_u32 s1, s77, s1
	v_cndmask_b32_e32 v1, v202, v1, vcc
	v_lshlrev_b32_e32 v42, 2, v1
	v_xor_b32_e32 v1, 2, v202
	v_cmp_lt_i32_e32 vcc, v1, v0
	v_lshlrev_b32_e32 v168, 2, v32
	v_lshl_add_u64 v[34:35], s[0:1], 0, v[168:169]
	v_cndmask_b32_e32 v1, v202, v1, vcc
	v_lshlrev_b32_e32 v43, 2, v1
	v_xor_b32_e32 v1, 1, v202
	v_cmp_lt_i32_e32 vcc, v1, v0
	v_lshlrev_b32_e32 v168, 1, v32
	v_lshl_add_u64 v[36:37], s[24:25], 0, v[168:169]
	v_cndmask_b32_e32 v0, v202, v1, vcc
	v_lshlrev_b32_e32 v44, 2, v0
	s_mov_b64 s[8:9], 0
	v_readfirstlane_b32 s40, v16
	v_mov_b32_e32 v180, v33
	v_mov_b32_e32 v181, v40
	v_mov_b32_e32 v182, v41
	v_mov_b32_e32 v183, v42
	v_mov_b32_e32 v184, v43
	v_mov_b32_e32 v185, v44
	v_lshlrev_b32_e32 v186, 4, v202
	v_lshlrev_b32_e32 v187, 3, v202
	global_load_dwordx4 v[0:3], v186, s[0:1]
	global_load_dwordx4 v[4:7], v186, s[0:1] offset:1024
	global_load_dwordx4 v[8:11], v186, s[0:1] offset:2048
	global_load_dwordx4 v[12:15], v186, s[0:1] offset:3072
	v_readlane_b32 s36, v248, 20
	v_readlane_b32 s37, v248, 21
	v_readlane_b32 s38, v248, 22
	v_readlane_b32 s39, v248, 23
	s_nop 0
	s_sub_u32 s12, s38, 0x4000000
	s_subb_u32 s13, s39, 0
	s_lshl_b32 s8, s40, 12
	v_add_u32_e32 v188, s8, v186
	s_cmp_lt_u32 s40, 0x4000
	s_cselect_b32 s44, s36, s12
	s_cselect_b32 s45, s37, s13
	s_cmp_lg_u64 s[2:3], 0
	s_cselect_b32 s44, s22, s44
	s_cselect_b32 s45, s23, s45
	s_add_i32 s8, s40, 0x800
	s_cmp_lt_u32 s8, 0x4400
	s_cselect_b32 s48, 1, 0
	s_cselect_b32 s9, 0x800000, 0
	s_cselect_b32 s8, s8, s40
	v_add_u32_e32 v189, s9, v188
	s_cmp_lt_u32 s8, 0x4000
	s_cselect_b32 s46, s36, s12
	s_cselect_b32 s47, s37, s13
	s_cmp_lg_u64 s[2:3], 0
	s_cselect_b32 s46, s22, s46
	s_cselect_b32 s47, s23, s47
	s_mov_b32 s51, 0x3a800000
	global_load_dwordx4 v[64:67], v188, s[44:45]
	global_load_dwordx4 v[68:71], v188, s[44:45] offset:1024
	global_load_dwordx4 v[72:75], v188, s[44:45] offset:2048
	global_load_dwordx4 v[76:79], v188, s[44:45] offset:3072
	global_load_dwordx4 v[80:83], v189, s[46:47]
	global_load_dwordx4 v[84:87], v189, s[46:47] offset:1024
	global_load_dwordx4 v[88:91], v189, s[46:47] offset:2048
	global_load_dwordx4 v[92:95], v189, s[46:47] offset:3072
	s_waitcnt vmcnt(0)
.Lp0n_loop:
	v_mov_b64_e32 v[32:33], v[64:65]
	v_mov_b64_e32 v[34:35], v[66:67]
	v_mov_b64_e32 v[36:37], v[68:69]
	v_mov_b64_e32 v[38:39], v[70:71]
	v_mov_b64_e32 v[40:41], v[72:73]
	v_mov_b64_e32 v[42:43], v[74:75]
	v_mov_b64_e32 v[44:45], v[76:77]
	v_mov_b64_e32 v[46:47], v[78:79]
	v_mov_b64_e32 v[48:49], v[80:81]
	v_mov_b64_e32 v[50:51], v[82:83]
	v_mov_b64_e32 v[52:53], v[84:85]
	v_mov_b64_e32 v[54:55], v[86:87]
	v_mov_b64_e32 v[56:57], v[88:89]
	v_mov_b64_e32 v[58:59], v[90:91]
	v_mov_b64_e32 v[60:61], v[92:93]
	v_mov_b64_e32 v[62:63], v[94:95]
	v_lshrrev_b32_e32 v194, 1, v188
	v_lshrrev_b32_e32 v195, 1, v189
	s_mov_b32 s49, s48
	s_add_i32 s41, s40, 0x1000
	s_cmp_lt_u32 s41, 0x4400
	s_cselect_b32 s50, 1, 0
	s_cbranch_scc0 .Lp0n_noload
	v_add_u32_e32 v188, 0x1000000, v188
	s_cmp_lt_u32 s41, 0x4000
	s_cselect_b32 s44, s36, s12
	s_cselect_b32 s45, s37, s13
	s_cmp_lg_u64 s[2:3], 0
	s_cselect_b32 s44, s22, s44
	s_cselect_b32 s45, s23, s45
	s_add_i32 s8, s41, 0x800
	s_cmp_lt_u32 s8, 0x4400
	s_cselect_b32 s48, 1, 0
	s_cselect_b32 s9, 0x800000, 0
	s_cselect_b32 s8, s8, s41
	v_add_u32_e32 v189, s9, v188
	s_cmp_lt_u32 s8, 0x4000
	s_cselect_b32 s46, s36, s12
	s_cselect_b32 s47, s37, s13
	s_cmp_lg_u64 s[2:3], 0
	s_cselect_b32 s46, s22, s46
	s_cselect_b32 s47, s23, s47
	global_load_dwordx4 v[64:67], v188, s[44:45]
	global_load_dwordx4 v[68:71], v188, s[44:45] offset:1024
	global_load_dwordx4 v[72:75], v188, s[44:45] offset:2048
	global_load_dwordx4 v[76:79], v188, s[44:45] offset:3072
	global_load_dwordx4 v[80:83], v189, s[46:47]
	global_load_dwordx4 v[84:87], v189, s[46:47] offset:1024
	global_load_dwordx4 v[88:91], v189, s[46:47] offset:2048
	global_load_dwordx4 v[92:95], v189, s[46:47] offset:3072
; DEV unsigned cvt_pk_bf16(float lo, float hi) { const f32x2_ v = {lo, hi}; return __builtin_bit_cast(unsigned, __builtin_convertvector(v, bf16x2n_)); }
; DEV void phase_p0(const Params& p, int l, unsigned char* smem) {
;     ...
; #pragma unroll
;     for (int k = 0; k < 2; ++k) {
; #pragma unroll
;       for (int i = 0; i < 4; ++i) ss[k] += x[k][i][0] * x[k][i][0] + x[k][i][1] * x[k][i][1] + x[k][i][2] * x[k][i][2] + x[k][i][3] * x[k][i][3];
;       ss[k] = wave_sum(ss[k]);
;     }
; #pragma unroll
;     for (int k = 0; k < 2; ++k) {
;       if (k == 1 && !v1) break;
;       const int r = rr[k];
;       const float rstd = rsqrtf(ss[k] * (1.0f / D) + 1e-6f);
; #pragma unroll
;       for (int i = 0; i < 4; ++i) {
;         const int col = i * 256 + lane * 4;
;         const f32x4 gv = *(const f32x4*)(g + col);
;         u32x2 w; w.x = cvt_pk_bf16(x[k][i][0] * rstd * gv[0], x[k][i][1] * rstd * gv[1]); w.y = cvt_pk_bf16(x[k][i][2] * rstd * gv[2], x[k][i][3] * rstd * gv[3]);
;         *(u32x2*)(H + (size_t)r * D + col) = w;
;       }
;     }
.Lp0n_noload:
	v_mul_f32_e32 v162, v32, v32
	v_mul_f32_e32 v163, v48, v48
	v_fmac_f32_e32 v162, v33, v33
	v_fmac_f32_e32 v163, v49, v49
	v_fmac_f32_e32 v162, v34, v34
	v_fmac_f32_e32 v163, v50, v50
	v_fmac_f32_e32 v162, v35, v35
	v_fmac_f32_e32 v163, v51, v51
	v_mov_b32_e32 v160, v162
	v_mov_b32_e32 v161, v163
	v_mul_f32_e32 v162, v36, v36
	v_mul_f32_e32 v163, v52, v52
	v_fmac_f32_e32 v162, v37, v37
	v_fmac_f32_e32 v163, v53, v53
	v_fmac_f32_e32 v162, v38, v38
	v_fmac_f32_e32 v163, v54, v54
	v_fmac_f32_e32 v162, v39, v39
	v_fmac_f32_e32 v163, v55, v55
	v_add_f32_e32 v160, v160, v162
	v_add_f32_e32 v161, v161, v163
	v_mul_f32_e32 v162, v40, v40
	v_mul_f32_e32 v163, v56, v56
	v_fmac_f32_e32 v162, v41, v41
	v_fmac_f32_e32 v163, v57, v57
	v_fmac_f32_e32 v162, v42, v42
	v_fmac_f32_e32 v163, v58, v58
	v_fmac_f32_e32 v162, v43, v43
	v_fmac_f32_e32 v163, v59, v59
	v_add_f32_e32 v160, v160, v162
	v_add_f32_e32 v161, v161, v163
	v_mul_f32_e32 v162, v44, v44
	v_mul_f32_e32 v163, v60, v60
	v_fmac_f32_e32 v162, v45, v45
	v_fmac_f32_e32 v163, v61, v61
	v_fmac_f32_e32 v162, v46, v46
	v_fmac_f32_e32 v163, v62, v62
	v_fmac_f32_e32 v162, v47, v47
	v_fmac_f32_e32 v163, v63, v63
	v_add_f32_e32 v160, v160, v162
	v_add_f32_e32 v161, v161, v163
	ds_bpermute_b32 v162, v180, v160
	ds_bpermute_b32 v163, v180, v161
	s_waitcnt lgkmcnt(0)
	v_add_f32_e32 v160, v160, v162
	v_add_f32_e32 v161, v161, v163
	ds_bpermute_b32 v162, v181, v160
	ds_bpermute_b32 v163, v181, v161
	s_waitcnt lgkmcnt(0)
	v_add_f32_e32 v160, v160, v162
	v_add_f32_e32 v161, v161, v163
	ds_bpermute_b32 v162, v182, v160
	ds_bpermute_b32 v163, v182, v161
	s_waitcnt lgkmcnt(0)
	v_add_f32_e32 v160, v160, v162
	v_add_f32_e32 v161, v161, v163
	ds_bpermute_b32 v162, v183, v160
	ds_bpermute_b32 v163, v183, v161
	s_waitcnt lgkmcnt(0)
	v_add_f32_e32 v160, v160, v162
	v_add_f32_e32 v161, v161, v163
	ds_bpermute_b32 v162, v184, v160
	ds_bpermute_b32 v163, v184, v161
	s_waitcnt lgkmcnt(0)
	v_add_f32_e32 v160, v160, v162
	v_add_f32_e32 v161, v161, v163
	ds_bpermute_b32 v162, v185, v160
	ds_bpermute_b32 v163, v185, v161
	s_waitcnt lgkmcnt(0)
	v_add_f32_e32 v160, v160, v162
	v_add_f32_e32 v161, v161, v163
	v_fma_f32 v162, v160, s51, v170
	v_fma_f32 v163, v161, s51, v170
	v_rsq_f32_e32 v166, v162
	v_rsq_f32_e32 v167, v163
	s_nop 0
	v_mul_f32_e32 v32, v32, v166
	v_mul_f32_e32 v33, v33, v166
	v_mul_f32_e32 v34, v34, v166
	v_mul_f32_e32 v35, v35, v166
	v_mul_f32_e32 v32, v32, v0
	v_mul_f32_e32 v33, v33, v1
	v_mul_f32_e32 v34, v34, v2
	v_mul_f32_e32 v35, v35, v3
	v_cvt_pk_bf16_f32 v96, v32, v33
	v_cvt_pk_bf16_f32 v97, v34, v35
	global_store_dwordx2 v194, v[96:97], s[24:25]
	v_mul_f32_e32 v36, v36, v166
	v_mul_f32_e32 v37, v37, v166
	v_mul_f32_e32 v38, v38, v166
	v_mul_f32_e32 v39, v39, v166
	v_mul_f32_e32 v36, v36, v4
	v_mul_f32_e32 v37, v37, v5
	v_mul_f32_e32 v38, v38, v6
	v_mul_f32_e32 v39, v39, v7
	v_cvt_pk_bf16_f32 v98, v36, v37
	v_cvt_pk_bf16_f32 v99, v38, v39
	global_store_dwordx2 v194, v[98:99], s[24:25] offset:512
	v_mul_f32_e32 v40, v40, v166
	v_mul_f32_e32 v41, v41, v166
	v_mul_f32_e32 v42, v42, v166
	v_mul_f32_e32 v43, v43, v166
	v_mul_f32_e32 v40, v40, v8
	v_mul_f32_e32 v41, v41, v9
	v_mul_f32_e32 v42, v42, v10
	v_mul_f32_e32 v43, v43, v11
	v_cvt_pk_bf16_f32 v100, v40, v41
	v_cvt_pk_bf16_f32 v101, v42, v43
	global_store_dwordx2 v194, v[100:101], s[24:25] offset:1024
	v_mul_f32_e32 v44, v44, v166
	v_mul_f32_e32 v45, v45, v166
	v_mul_f32_e32 v46, v46, v166
	v_mul_f32_e32 v47, v47, v166
	v_mul_f32_e32 v44, v44, v12
	v_mul_f32_e32 v45, v45, v13
	v_mul_f32_e32 v46, v46, v14
	v_mul_f32_e32 v47, v47, v15
	v_cvt_pk_bf16_f32 v102, v44, v45
	v_cvt_pk_bf16_f32 v103, v46, v47
	global_store_dwordx2 v194, v[102:103], s[24:25] offset:1536
	s_cmp_eq_u32 s49, 0
	s_cbranch_scc1 .Lp0n_skip1
	v_mul_f32_e32 v48, v48, v167
	v_mul_f32_e32 v49, v49, v167
	v_mul_f32_e32 v50, v50, v167
	v_mul_f32_e32 v51, v51, v167
	v_mul_f32_e32 v48, v48, v0
	v_mul_f32_e32 v49, v49, v1
	v_mul_f32_e32 v50, v50, v2
	v_mul_f32_e32 v51, v51, v3
	v_cvt_pk_bf16_f32 v104, v48, v49
	v_cvt_pk_bf16_f32 v105, v50, v51
	global_store_dwordx2 v195, v[104:105], s[24:25]
	v_mul_f32_e32 v52, v52, v167
	v_mul_f32_e32 v53, v53, v167
	v_mul_f32_e32 v54, v54, v167
	v_mul_f32_e32 v55, v55, v167
	v_mul_f32_e32 v52, v52, v4
	v_mul_f32_e32 v53, v53, v5
	v_mul_f32_e32 v54, v54, v6
	v_mul_f32_e32 v55, v55, v7
	v_cvt_pk_bf16_f32 v106, v52, v53
	v_cvt_pk_bf16_f32 v107, v54, v55
	global_store_dwordx2 v195, v[106:107], s[24:25] offset:512
	v_mul_f32_e32 v56, v56, v167
	v_mul_f32_e32 v57, v57, v167
	v_mul_f32_e32 v58, v58, v167
	v_mul_f32_e32 v59, v59, v167
	v_mul_f32_e32 v56, v56, v8
	v_mul_f32_e32 v57, v57, v9
	v_mul_f32_e32 v58, v58, v10
	v_mul_f32_e32 v59, v59, v11
	v_cvt_pk_bf16_f32 v108, v56, v57
	v_cvt_pk_bf16_f32 v109, v58, v59
	global_store_dwordx2 v195, v[108:109], s[24:25] offset:1024
	v_mul_f32_e32 v60, v60, v167
	v_mul_f32_e32 v61, v61, v167
	v_mul_f32_e32 v62, v62, v167
	v_mul_f32_e32 v63, v63, v167
	v_mul_f32_e32 v60, v60, v12
	v_mul_f32_e32 v61, v61, v13
	v_mul_f32_e32 v62, v62, v14
	v_mul_f32_e32 v63, v63, v15
	v_cvt_pk_bf16_f32 v110, v60, v61
	v_cvt_pk_bf16_f32 v111, v62, v63
	global_store_dwordx2 v195, v[110:111], s[24:25] offset:1536
.Lp0n_skip1:
	s_cmp_eq_u32 s50, 0
	s_cbranch_scc1 .Lp0n_exit
	s_mov_b32 s40, s41
	s_waitcnt vmcnt(8)
	s_branch .Lp0n_loop
.Lp0n_exit:
	s_getpc_b64 s[98:99]
.Lpost_getpc5:
	s_add_u32 s98, s98, (.LBB0_7-.Lpost_getpc5)&4294967295
	s_addc_u32 s99, s99, (.LBB0_7-.Lpost_getpc5)>>32
	s_setpc_b64 s[98:99]
.LBB0_559:
	s_endpgm
